# grid barrier release flattened: non-leader workgroups poll the cross-XCD release word directly, per-XCD release add dropped
# baseline (speedup 1.0000x reference)
.LBB0_94:
	s_or_b64 exec, exec, s[4:5]
	v_cvt_f32_u32_e32 v4, v2
	s_waitcnt vmcnt(0)
	v_readfirstlane_b32 s3, v3
	v_sub_u32_e32 v3, 0, v2
	v_rcp_iflag_f32_e32 v4, v4
	v_add_u32_e32 v5, s3, v1
	v_mul_f32_e32 v4, 0x4f7ffffe, v4
	v_cvt_u32_f32_e32 v4, v4
	v_mul_lo_u32 v1, v3, v4
	v_mul_hi_u32 v1, v4, v1
	v_add_u32_e32 v1, v4, v1
	v_mul_hi_u32 v1, v5, v1
	v_mul_lo_u32 v3, v1, v2
	v_sub_u32_e32 v3, v5, v3
	v_add_u32_e32 v4, 1, v1
	v_sub_u32_e32 v6, v3, v2
	v_cmp_ge_u32_e32 vcc, v3, v2
	s_nop 1
	v_cndmask_b32_e32 v1, v1, v4, vcc
	v_cndmask_b32_e32 v3, v3, v6, vcc
	v_add_u32_e32 v4, 1, v1
	v_cmp_ge_u32_e32 vcc, v3, v2
	v_add_u32_e32 v3, 1, v5
	s_nop 0
	v_cndmask_b32_e32 v1, v1, v4, vcc
	v_mul_lo_u32 v4, v2, v1
	v_add_u32_e32 v2, v4, v2
	v_cmp_ne_u32_e32 vcc, v3, v2
	s_and_saveexec_b64 s[4:5], vcc
	s_xor_b64 s[4:5], exec, s[4:5]
	s_cbranch_execz .LBB0_108
	s_mov_b32 s12, s24
	s_waitcnt lgkmcnt(0)
	v_mov_b32_e32 v0, 0
	s_mov_b32 s13, s25
	s_nop 4
	global_load_dword v2, v0, s[12:13] sc1
	s_waitcnt vmcnt(0)
	v_cmp_eq_u32_e32 vcc, v2, v1
	s_and_saveexec_b64 s[12:13], vcc
	s_cbranch_execz .LBB0_107
	s_mov_b32 s3, 1
	s_mov_b64 s[14:15], 0
	s_branch .LBB0_98

.LBB0_102:
	s_mov_b32 s20, s24
	s_mov_b32 s21, s25
	s_add_i32 s3, s3, 1
	s_mov_b64 s[22:23], -1
	s_nop 2
	global_load_dword v2, v0, s[20:21] sc1
	s_waitcnt vmcnt(0)
	v_cmp_ne_u32_e32 vcc, v2, v1
	s_orn2_b64 s[20:21], vcc, exec
	s_branch .LBB0_97

.LBB0_125:
	s_or_b64 exec, exec, s[4:5]
	s_mov_b64 s[4:5], exec
	v_mbcnt_lo_u32_b32 v0, s4, 0
	v_mbcnt_hi_u32_b32 v0, s5, v0
	v_cmp_eq_u32_e32 vcc, 0, v0
	s_waitcnt vmcnt(0)
	buffer_inv sc1
	s_and_saveexec_b64 s[12:13], vcc
	s_cbranch_execz .LBB0_127
	s_bcnt1_i32_b64 s3, s[4:5]
	v_readlane_b32 s4, v232, 43
	v_mov_b32_e32 v0, 0
	v_mov_b32_e32 v1, s3
	v_readlane_b32 s5, v232, 44
	s_nop 4
	s_nop 0

.LBB0_274:
	s_or_b64 exec, exec, s[4:5]
	v_cvt_f32_u32_e32 v4, v2
	s_waitcnt vmcnt(0)
	v_readfirstlane_b32 s4, v3
	v_sub_u32_e32 v3, 0, v2
	v_rcp_iflag_f32_e32 v4, v4
	v_add_u32_e32 v5, s4, v1
	v_mul_f32_e32 v4, 0x4f7ffffe, v4
	v_cvt_u32_f32_e32 v4, v4
	v_mul_lo_u32 v1, v3, v4
	v_mul_hi_u32 v1, v4, v1
	v_add_u32_e32 v1, v4, v1
	v_mul_hi_u32 v1, v5, v1
	v_mul_lo_u32 v3, v1, v2
	v_sub_u32_e32 v3, v5, v3
	v_add_u32_e32 v4, 1, v1
	v_cmp_ge_u32_e32 vcc, v3, v2
	s_nop 1
	v_cndmask_b32_e32 v1, v1, v4, vcc
	v_sub_u32_e32 v4, v3, v2
	v_cndmask_b32_e32 v3, v3, v4, vcc
	v_add_u32_e32 v4, 1, v1
	v_cmp_ge_u32_e32 vcc, v3, v2
	v_add_u32_e32 v3, 1, v5
	s_nop 0
	v_cndmask_b32_e32 v1, v1, v4, vcc
	v_mul_lo_u32 v4, v2, v1
	v_add_u32_e32 v2, v4, v2
	v_cmp_ne_u32_e32 vcc, v3, v2
	s_and_saveexec_b64 s[4:5], vcc
	s_xor_b64 s[4:5], exec, s[4:5]
	s_cbranch_execz .LBB0_288
	v_readlane_b32 s12, v232, 47
	s_waitcnt lgkmcnt(0)
	v_mov_b32_e32 v0, 0
	v_readlane_b32 s13, v232, 48
	s_nop 4
	global_load_dword v2, v0, s[12:13] sc1
	s_waitcnt vmcnt(0)
	v_cmp_eq_u32_e32 vcc, v2, v1
	s_and_saveexec_b64 s[12:13], vcc
	s_cbranch_execz .LBB0_287
	s_mov_b32 s24, 1
	s_mov_b64 s[14:15], 0
	s_branch .LBB0_278

.LBB0_282:
	v_readlane_b32 s20, v232, 47
	v_readlane_b32 s21, v232, 48
	s_add_i32 s24, s24, 1
	s_mov_b64 s[22:23], -1
	s_nop 2
	global_load_dword v2, v0, s[20:21] sc1
	s_waitcnt vmcnt(0)
	v_cmp_ne_u32_e32 vcc, v2, v1
	s_orn2_b64 s[20:21], vcc, exec
	s_branch .LBB0_277

.LBB0_305:
	s_or_b64 exec, exec, s[4:5]
	s_mov_b64 s[4:5], exec
	v_mbcnt_lo_u32_b32 v0, s4, 0
	v_mbcnt_hi_u32_b32 v0, s5, v0
	v_cmp_eq_u32_e32 vcc, 0, v0
	s_waitcnt vmcnt(0)
	buffer_inv sc1
	s_and_saveexec_b64 s[12:13], vcc
	s_cbranch_execz .LBB0_307
	s_bcnt1_i32_b64 s4, s[4:5]
	v_mov_b32_e32 v1, s4
	v_readlane_b32 s4, v232, 43
	v_mov_b32_e32 v0, 0
	v_readlane_b32 s5, v232, 44
	s_nop 4
	s_nop 0

.LBB0_495:
	v_readlane_b32 s26, v232, 47
	v_readlane_b32 s27, v232, 48
	s_add_i32 s24, s24, 1
	s_mov_b64 s[44:45], -1
	s_nop 2
	global_load_dword v2, v0, s[26:27] sc1
	s_waitcnt vmcnt(0)
	v_cmp_ne_u32_e32 vcc, v2, v1
	s_orn2_b64 s[42:43], vcc, exec
	s_branch .LBB0_490

.LBB0_683:
	s_or_b64 exec, exec, s[4:5]
	v_cvt_f32_u32_e32 v4, v2
	s_waitcnt vmcnt(0)
	v_readfirstlane_b32 s4, v3
	v_sub_u32_e32 v3, 0, v2
	v_rcp_iflag_f32_e32 v4, v4
	v_add_u32_e32 v5, s4, v1
	v_mul_f32_e32 v4, 0x4f7ffffe, v4
	v_cvt_u32_f32_e32 v4, v4
	v_mul_lo_u32 v1, v3, v4
	v_mul_hi_u32 v1, v4, v1
	v_add_u32_e32 v1, v4, v1
	v_mul_hi_u32 v1, v5, v1
	v_mul_lo_u32 v3, v1, v2
	v_sub_u32_e32 v3, v5, v3
	v_add_u32_e32 v4, 1, v1
	v_cmp_ge_u32_e32 vcc, v3, v2
	s_nop 1
	v_cndmask_b32_e32 v1, v1, v4, vcc
	v_sub_u32_e32 v4, v3, v2
	v_cndmask_b32_e32 v3, v3, v4, vcc
	v_add_u32_e32 v4, 1, v1
	v_cmp_ge_u32_e32 vcc, v3, v2
	v_add_u32_e32 v3, 1, v5
	s_nop 0
	v_cndmask_b32_e32 v1, v1, v4, vcc
	v_mul_lo_u32 v4, v2, v1
	v_add_u32_e32 v2, v4, v2
	v_cmp_ne_u32_e32 vcc, v3, v2
	s_and_saveexec_b64 s[4:5], vcc
	s_xor_b64 s[4:5], exec, s[4:5]
	s_cbranch_execz .LBB0_697
	v_readlane_b32 s14, v232, 47
	s_waitcnt lgkmcnt(0)
	v_mov_b32_e32 v0, 0
	v_readlane_b32 s15, v232, 48
	s_nop 4
	global_load_dword v2, v0, s[14:15] sc1
	s_waitcnt vmcnt(0)
	v_cmp_eq_u32_e32 vcc, v2, v1
	s_and_saveexec_b64 s[14:15], vcc
	s_cbranch_execz .LBB0_696
	s_mov_b32 s24, 1
	s_mov_b64 s[42:43], 0
	s_branch .LBB0_687

.LBB0_691:
	v_readlane_b32 s26, v232, 47
	v_readlane_b32 s27, v232, 48
	s_add_i32 s24, s24, 1
	s_mov_b64 s[48:49], -1
	s_nop 2
	global_load_dword v2, v0, s[26:27] sc1
	s_waitcnt vmcnt(0)
	v_cmp_ne_u32_e32 vcc, v2, v1
	s_orn2_b64 s[46:47], vcc, exec
	s_branch .LBB0_686

.LBB0_714:
	s_or_b64 exec, exec, s[4:5]
	s_mov_b64 s[4:5], exec
	v_mbcnt_lo_u32_b32 v0, s4, 0
	v_mbcnt_hi_u32_b32 v0, s5, v0
	v_cmp_eq_u32_e32 vcc, 0, v0
	s_waitcnt vmcnt(0)
	buffer_inv sc1
	s_and_saveexec_b64 s[14:15], vcc
	s_cbranch_execz .LBB0_716
	s_bcnt1_i32_b64 s4, s[4:5]
	v_mov_b32_e32 v1, s4
	v_readlane_b32 s4, v232, 43
	v_mov_b32_e32 v0, 0
	v_readlane_b32 s5, v232, 44
	s_nop 4
	s_nop 0

.LBB0_749:
	s_or_b64 exec, exec, s[4:5]
	v_cvt_f32_u32_e32 v4, v2
	s_waitcnt vmcnt(0)
	v_readfirstlane_b32 s4, v3
	v_sub_u32_e32 v3, 0, v2
	v_rcp_iflag_f32_e32 v4, v4
	v_add_u32_e32 v5, s4, v1
	v_mul_f32_e32 v4, 0x4f7ffffe, v4
	v_cvt_u32_f32_e32 v4, v4
	v_mul_lo_u32 v1, v3, v4
	v_mul_hi_u32 v1, v4, v1
	v_add_u32_e32 v1, v4, v1
	v_mul_hi_u32 v1, v5, v1
	v_mul_lo_u32 v3, v1, v2
	v_sub_u32_e32 v3, v5, v3
	v_add_u32_e32 v4, 1, v1
	v_cmp_ge_u32_e32 vcc, v3, v2
	s_nop 1
	v_cndmask_b32_e32 v1, v1, v4, vcc
	v_sub_u32_e32 v4, v3, v2
	v_cndmask_b32_e32 v3, v3, v4, vcc
	v_add_u32_e32 v4, 1, v1
	v_cmp_ge_u32_e32 vcc, v3, v2
	v_add_u32_e32 v3, 1, v5
	s_nop 0
	v_cndmask_b32_e32 v1, v1, v4, vcc
	v_mul_lo_u32 v4, v2, v1
	v_add_u32_e32 v2, v4, v2
	v_cmp_ne_u32_e32 vcc, v3, v2
	s_and_saveexec_b64 s[4:5], vcc
	s_xor_b64 s[4:5], exec, s[4:5]
	s_cbranch_execz .LBB0_763
	v_readlane_b32 s14, v232, 47
	s_waitcnt lgkmcnt(0)
	v_mov_b32_e32 v0, 0
	v_readlane_b32 s15, v232, 48
	s_nop 4
	global_load_dword v2, v0, s[14:15] sc1
	s_waitcnt vmcnt(0)
	v_cmp_eq_u32_e32 vcc, v2, v1
	s_and_saveexec_b64 s[14:15], vcc
	s_cbranch_execz .LBB0_762
	s_mov_b32 s24, 1
	s_mov_b64 s[38:39], 0
	s_branch .LBB0_753

.LBB0_757:
	v_readlane_b32 s26, v232, 47
	v_readlane_b32 s27, v232, 48
	s_add_i32 s24, s24, 1
	s_mov_b64 s[46:47], -1
	s_nop 2
	global_load_dword v2, v0, s[26:27] sc1
	s_waitcnt vmcnt(0)
	v_cmp_ne_u32_e32 vcc, v2, v1
	s_orn2_b64 s[44:45], vcc, exec
	s_branch .LBB0_752

.LBB0_1190:
	s_or_b64 exec, exec, s[4:5]
	v_cvt_f32_u32_e32 v4, v2
	s_waitcnt vmcnt(0)
	v_readfirstlane_b32 s4, v3
	v_sub_u32_e32 v3, 0, v2
	v_rcp_iflag_f32_e32 v4, v4
	v_add_u32_e32 v5, s4, v1
	v_mul_f32_e32 v4, 0x4f7ffffe, v4
	v_cvt_u32_f32_e32 v4, v4
	v_mul_lo_u32 v1, v3, v4
	v_mul_hi_u32 v1, v4, v1
	v_add_u32_e32 v1, v4, v1
	v_mul_hi_u32 v1, v5, v1
	v_mul_lo_u32 v3, v1, v2
	v_sub_u32_e32 v3, v5, v3
	v_add_u32_e32 v4, 1, v1
	v_cmp_ge_u32_e32 vcc, v3, v2
	s_nop 1
	v_cndmask_b32_e32 v1, v1, v4, vcc
	v_sub_u32_e32 v4, v3, v2
	v_cndmask_b32_e32 v3, v3, v4, vcc
	v_add_u32_e32 v4, 1, v1
	v_cmp_ge_u32_e32 vcc, v3, v2
	v_add_u32_e32 v3, 1, v5
	s_nop 0
	v_cndmask_b32_e32 v1, v1, v4, vcc
	v_mul_lo_u32 v4, v2, v1
	v_add_u32_e32 v2, v4, v2
	v_cmp_ne_u32_e32 vcc, v3, v2
	s_and_saveexec_b64 s[4:5], vcc
	s_xor_b64 s[4:5], exec, s[4:5]
	s_cbranch_execz .LBB0_1204
	v_readlane_b32 s14, v232, 47
	s_waitcnt lgkmcnt(0)
	v_mov_b32_e32 v0, 0
	v_readlane_b32 s15, v232, 48
	s_nop 4
	global_load_dword v2, v0, s[14:15] sc1
	s_waitcnt vmcnt(0)
	v_cmp_eq_u32_e32 vcc, v2, v1
	s_and_saveexec_b64 s[14:15], vcc
	s_cbranch_execz .LBB0_1203
	s_mov_b32 s24, 1
	s_mov_b64 s[20:21], 0
	s_branch .LBB0_1194

.LBB0_1198:
	v_readlane_b32 s26, v232, 47
	v_readlane_b32 s27, v232, 48
	s_add_i32 s24, s24, 1
	s_mov_b64 s[42:43], -1
	s_nop 2
	global_load_dword v2, v0, s[26:27] sc1
	s_waitcnt vmcnt(0)
	v_cmp_ne_u32_e32 vcc, v2, v1
	s_orn2_b64 s[40:41], vcc, exec
	s_branch .LBB0_1193

.LBB0_1280:
	s_or_b64 exec, exec, s[4:5]
	v_cvt_f32_u32_e32 v4, v2
	s_waitcnt vmcnt(0)
	v_readfirstlane_b32 s4, v3
	v_sub_u32_e32 v3, 0, v2
	v_rcp_iflag_f32_e32 v4, v4
	v_add_u32_e32 v5, s4, v1
	v_mul_f32_e32 v4, 0x4f7ffffe, v4
	v_cvt_u32_f32_e32 v4, v4
	v_mul_lo_u32 v1, v3, v4
	v_mul_hi_u32 v1, v4, v1
	v_add_u32_e32 v1, v4, v1
	v_mul_hi_u32 v1, v5, v1
	v_mul_lo_u32 v3, v1, v2
	v_sub_u32_e32 v3, v5, v3
	v_add_u32_e32 v4, 1, v1
	v_cmp_ge_u32_e32 vcc, v3, v2
	s_nop 1
	v_cndmask_b32_e32 v1, v1, v4, vcc
	v_sub_u32_e32 v4, v3, v2
	v_cndmask_b32_e32 v3, v3, v4, vcc
	v_add_u32_e32 v4, 1, v1
	v_cmp_ge_u32_e32 vcc, v3, v2
	v_add_u32_e32 v3, 1, v5
	s_nop 0
	v_cndmask_b32_e32 v1, v1, v4, vcc
	v_mul_lo_u32 v4, v2, v1
	v_add_u32_e32 v2, v4, v2
	v_cmp_ne_u32_e32 vcc, v3, v2
	s_and_saveexec_b64 s[4:5], vcc
	s_xor_b64 s[4:5], exec, s[4:5]
	s_cbranch_execz .LBB0_1294
	v_readlane_b32 s8, v232, 47
	s_waitcnt lgkmcnt(0)
	v_mov_b32_e32 v0, 0
	v_readlane_b32 s9, v232, 48
	s_nop 4
	global_load_dword v2, v0, s[8:9] sc1
	s_waitcnt vmcnt(0)
	v_cmp_eq_u32_e32 vcc, v2, v1
	s_and_saveexec_b64 s[8:9], vcc
	s_cbranch_execz .LBB0_1293
	s_mov_b32 s22, 1
	s_mov_b64 s[10:11], 0
	s_branch .LBB0_1284

.LBB0_1288:
	v_readlane_b32 s16, v232, 47
	v_readlane_b32 s17, v232, 48
	s_add_i32 s22, s22, 1
	s_mov_b64 s[18:19], -1
	s_nop 2
	global_load_dword v2, v0, s[16:17] sc1
	s_waitcnt vmcnt(0)
	v_cmp_ne_u32_e32 vcc, v2, v1
	s_orn2_b64 s[16:17], vcc, exec
	s_branch .LBB0_1283

.LBB0_1311:
	s_or_b64 exec, exec, s[4:5]
	s_mov_b64 s[4:5], exec
	v_mbcnt_lo_u32_b32 v0, s4, 0
	v_mbcnt_hi_u32_b32 v0, s5, v0
	v_cmp_eq_u32_e32 vcc, 0, v0
	s_waitcnt vmcnt(0)
	buffer_inv sc1
	s_and_saveexec_b64 s[8:9], vcc
	s_cbranch_execz .LBB0_1313
	s_bcnt1_i32_b64 s4, s[4:5]
	v_mov_b32_e32 v1, s4
	v_readlane_b32 s4, v232, 43
	v_mov_b32_e32 v0, 0
	v_readlane_b32 s5, v232, 44
	s_nop 4
	s_nop 0
